# prep0 per-token loop: extra two-ahead loads of the next-next token's q/k/v rows into scratch registers to warm L2 (real one-ahead loads then hit L2); latch waits bumped by 3
# speedup vs baseline: 1.0063x; 1.0063x over previous
.LBB0_987:
	s_or_b64 exec, exec, s[18:19]
	s_and_b64 s[0:1], exec, s[10:11]
	v_readlane_b32 s10, v252, 62
	v_readlane_b32 s11, v252, 63
	s_or_b64 s[28:29], s[0:1], s[28:29]
	v_readlane_b32 s0, v252, 38
	v_lshl_add_u64 v[62:63], v[62:63], 0, s[10:11]
	v_readlane_b32 s10, v253, 2
	v_readlane_b32 s1, v252, 39
	v_readlane_b32 s11, v253, 3
	s_waitcnt vmcnt(6)
	v_mov_b64_e32 v[30:31], v[14:15]
	s_waitcnt vmcnt(5)
	v_mov_b64_e32 v[26:27], v[22:23]
	s_waitcnt vmcnt(4) lgkmcnt(4)
	v_mov_b64_e32 v[8:9], v[16:17]
	v_lshl_add_u64 v[60:61], v[60:61], 0, s[0:1]
	v_lshl_add_u64 v[58:59], v[58:59], 0, s[0:1]
	v_lshl_add_u64 v[66:67], v[66:67], 0, s[10:11]
	v_lshl_add_u64 v[68:69], v[68:69], 0, s[0:1]
	v_mov_b64_e32 v[28:29], v[12:13]
	v_mov_b64_e32 v[24:25], v[20:21]
	v_mov_b64_e32 v[10:11], v[18:19]
	v_mov_b32_e32 v64, v65
	s_andn2_b64 exec, exec, s[28:29]
	s_cbranch_execz .LBB0_999
.LBB0_988:
	v_readlane_b32 s0, v253, 0
	v_readlane_b32 s1, v253, 1
	s_nop 0
	v_add_u32_e32 v65, s0, v64
	s_mov_b32 s0, 0xa000
	v_cmp_gt_i32_e32 vcc, s0, v65
	s_mov_b32 s0, 0x9fff
	v_cmp_lt_i32_e64 s[10:11], s0, v65
	s_and_saveexec_b64 s[18:19], vcc
	s_cbranch_execz .LBB0_990
	v_readlane_b32 s0, v253, 14
	v_readlane_b32 s1, v253, 15
	s_nop 1
	v_lshl_add_u64 v[14:15], s[0:1], 0, v[58:59]
	v_add_co_u32_e32 v16, vcc, 0xf281000, v14
	v_lshl_add_u64 v[12:13], s[0:1], 0, v[60:61]
	s_nop 0
	v_addc_co_u32_e32 v17, vcc, 0, v15, vcc
	v_readlane_b32 s98, v252, 38
	v_readlane_b32 s99, v252, 39
	s_nop 1
	v_lshl_add_u64 v[244:245], v[12:13], 0, s[98:99]
	v_lshl_add_u64 v[246:247], v[16:17], 0, s[98:99]
	global_load_dwordx4 v[12:15], v[12:13], off
	s_nop 0
	global_load_dwordx4 v[20:23], v[16:17], off offset:1024
	s_nop 0
	global_load_dwordx4 v[16:19], v[16:17], off offset:1280
	global_load_dwordx4 v[240:243], v[244:245], off
	global_load_dwordx4 v[240:243], v[246:247], off offset:1024
	global_load_dwordx4 v[240:243], v[246:247], off offset:1280
